# speedup vs baseline: 1.0134x; 1.0053x over previous
; __device__ __forceinline__ unsigned pk2(float lo, float hi) { return f2bf(lo) | (f2bf(hi) << 16); }
; __device__ __forceinline__ float gelu_tanh(float x) {
;     const float u = 0.7978845608028654f * (x + 0.044715f * x * x * x);
;     const float e = __expf(2.0f * u);
;     const float th = 1.0f - 2.0f * __builtin_amdgcn_rcpf(e + 1.0f);
;     return 0.5f * x * (1.0f + th);
; }
; __device__ __forceinline__ void gmlp_fast(KArgs ap, int l, LAS unsigned char* lds, const Ctx cx) {
;     ...
;             const size_t t = t0 + tl; const float bsv = bsp[g * 128 + tl];
;             const bf16_t* zu = z + t * DIN + ZGU + g * 128 + 4 * hh; bf16_t* yo = y + t * DM + YG + g * 128 + 4 * hh;
; #pragma unroll
;             for (int ht = 0; ht < 4; ++ht)
; #pragma unroll
;                 for (int q4 = 0; q4 < 4; ++q4) { const u32x2 uu = *(const u32x2*)(zu + ht * 32 + 8 * q4);
;                     const float o0 = gelu_tanh(bflo(uu.x)) * (acc[ht][4 * q4] + bsv), o1 = gelu_tanh(bfhi(uu.x)) * (acc[ht][4 * q4 + 1] + bsv);
;                     const float o2 = gelu_tanh(bflo(uu.y)) * (acc[ht][4 * q4 + 2] + bsv), o3 = gelu_tanh(bfhi(uu.y)) * (acc[ht][4 * q4 + 3] + bsv);
;                     u32x2 w; w.x = pk2(o0, o1); w.y = pk2(o2, o3); *(u32x2*)(yo + ht * 32 + 8 * q4) = w; }
.LBB0_160:
	s_lshl_b32 s20, s20, 7
	s_ashr_i32 s21, s20, 31
	v_or_b32_e32 v64, s20, v80
	s_lshl_b64 s[20:21], s[20:21], 1
	v_lshl_add_u64 v[68:69], v[94:95], 0, s[20:21]
	global_load_dwordx2 v[70:71], v[68:69], off offset:3584
	v_ashrrev_i32_e32 v65, 31, v64
	v_lshl_add_u64 v[64:65], v[64:65], 2, s[14:15]
	global_load_dword v64, v[64:65], off
	global_load_dwordx2 v[200:201], v[68:69], off offset:3600
	global_load_dwordx2 v[202:203], v[68:69], off offset:3616
	global_load_dwordx2 v[204:205], v[68:69], off offset:3632
	global_load_dwordx2 v[206:207], v[68:69], off offset:3648
	global_load_dwordx2 v[208:209], v[68:69], off offset:3664
	global_load_dwordx2 v[210:211], v[68:69], off offset:3680
	global_load_dwordx2 v[212:213], v[68:69], off offset:3696
	global_load_dwordx2 v[214:215], v[68:69], off offset:3712
	global_load_dwordx2 v[216:217], v[68:69], off offset:3728
	global_load_dwordx2 v[218:219], v[68:69], off offset:3744
	global_load_dwordx2 v[220:221], v[68:69], off offset:3760
	global_load_dwordx2 v[222:223], v[68:69], off offset:3776
	global_load_dwordx2 v[224:225], v[68:69], off offset:3792
	global_load_dwordx2 v[226:227], v[68:69], off offset:3808
	global_load_dwordx2 v[228:229], v[68:69], off offset:3824
	v_lshl_add_u64 v[66:67], v[96:97], 0, s[20:21]
	s_mov_b32 s13, 1
	s_mov_b64 s[20:21], 0
	s_and_b64 vcc, exec, s[0:1]
	s_waitcnt vmcnt(14)
	v_lshlrev_b32_e32 v113, 16, v70
	v_and_b32_e32 v114, 0xffff0000, v70
	v_lshlrev_b32_e32 v115, 16, v71
	v_and_b32_e32 v116, 0xffff0000, v71
	v_lshlrev_b32_e32 v117, 16, v200
	v_and_b32_e32 v118, 0xffff0000, v200
	v_lshlrev_b32_e32 v119, 16, v201
	v_and_b32_e32 v120, 0xffff0000, v201
	v_mul_f32_e32 v121, 0x3d372713, v113
	v_mul_f32_e32 v122, 0x3d372713, v114
	v_mul_f32_e32 v123, 0x3d372713, v115
	v_mul_f32_e32 v124, 0x3d372713, v116
	v_mul_f32_e32 v125, 0x3d372713, v117
	v_mul_f32_e32 v126, 0x3d372713, v118
	v_mul_f32_e32 v127, 0x3d372713, v119
	v_mul_f32_e32 v128, 0x3d372713, v120
	v_mul_f32_e32 v121, v121, v113
	v_mul_f32_e32 v122, v122, v114
	v_mul_f32_e32 v123, v123, v115
	v_mul_f32_e32 v124, v124, v116
	v_mul_f32_e32 v125, v125, v117
	v_mul_f32_e32 v126, v126, v118
	v_mul_f32_e32 v127, v127, v119
	v_mul_f32_e32 v128, v128, v120
	v_fma_f32 v121, v121, v113, v113
	v_fma_f32 v122, v122, v114, v114
	v_fma_f32 v123, v123, v115, v115
	v_fma_f32 v124, v124, v116, v116
	v_fma_f32 v125, v125, v117, v117
	v_fma_f32 v126, v126, v118, v118
	v_fma_f32 v127, v127, v119, v119
	v_fma_f32 v128, v128, v120, v120
	v_mul_f32_e32 v121, 0x3f4c422a, v121
	v_mul_f32_e32 v122, 0x3f4c422a, v122
	v_mul_f32_e32 v123, 0x3f4c422a, v123
	v_mul_f32_e32 v124, 0x3f4c422a, v124
	v_mul_f32_e32 v125, 0x3f4c422a, v125
	v_mul_f32_e32 v126, 0x3f4c422a, v126
	v_mul_f32_e32 v127, 0x3f4c422a, v127
	v_mul_f32_e32 v128, 0x3f4c422a, v128
	v_add_f32_e32 v121, v121, v121
	v_add_f32_e32 v122, v122, v122
	v_add_f32_e32 v123, v123, v123
	v_add_f32_e32 v124, v124, v124
	v_add_f32_e32 v125, v125, v125
	v_add_f32_e32 v126, v126, v126
	v_add_f32_e32 v127, v127, v127
	v_add_f32_e32 v128, v128, v128
	v_mul_f32_e32 v121, 0x3fb8aa3b, v121
	v_mul_f32_e32 v122, 0x3fb8aa3b, v122
	v_mul_f32_e32 v123, 0x3fb8aa3b, v123
	v_mul_f32_e32 v124, 0x3fb8aa3b, v124
	v_mul_f32_e32 v125, 0x3fb8aa3b, v125
	v_mul_f32_e32 v126, 0x3fb8aa3b, v126
	v_mul_f32_e32 v127, 0x3fb8aa3b, v127
	v_mul_f32_e32 v128, 0x3fb8aa3b, v128
	v_exp_f32_e32 v121, v121
	v_exp_f32_e32 v122, v122
	v_exp_f32_e32 v123, v123
	v_exp_f32_e32 v124, v124
	v_exp_f32_e32 v125, v125
	v_exp_f32_e32 v126, v126
	v_exp_f32_e32 v127, v127
	v_exp_f32_e32 v128, v128
	v_mul_f32_e32 v129, 0.5, v113
	v_mul_f32_e32 v130, 0.5, v114
	v_mul_f32_e32 v131, 0.5, v115
	v_mul_f32_e32 v132, 0.5, v116
	v_mul_f32_e32 v133, 0.5, v117
	v_mul_f32_e32 v134, 0.5, v118
	v_mul_f32_e32 v135, 0.5, v119
	v_mul_f32_e32 v138, 0.5, v120
	v_add_f32_e32 v121, 1.0, v121
	v_add_f32_e32 v122, 1.0, v122
	v_add_f32_e32 v123, 1.0, v123
	v_add_f32_e32 v124, 1.0, v124
	v_add_f32_e32 v125, 1.0, v125
	v_add_f32_e32 v126, 1.0, v126
	v_add_f32_e32 v127, 1.0, v127
	v_add_f32_e32 v128, 1.0, v128
	v_rcp_f32_e32 v121, v121
	v_rcp_f32_e32 v122, v122
	v_rcp_f32_e32 v123, v123
	v_rcp_f32_e32 v124, v124
	v_rcp_f32_e32 v125, v125
	v_rcp_f32_e32 v126, v126
	v_rcp_f32_e32 v127, v127
	v_rcp_f32_e32 v128, v128
	v_add_f32_e32 v48, v48, v64
	v_add_f32_e32 v49, v49, v64
	v_add_f32_e32 v50, v50, v64
	v_add_f32_e32 v51, v51, v64
	v_add_f32_e32 v52, v52, v64
	v_add_f32_e32 v53, v53, v64
	v_add_f32_e32 v54, v54, v64
	v_add_f32_e32 v55, v55, v64
	v_fma_f32 v121, v121, -2.0, 1.0
	v_fma_f32 v122, v122, -2.0, 1.0
	v_fma_f32 v123, v123, -2.0, 1.0
	v_fma_f32 v124, v124, -2.0, 1.0
	v_fma_f32 v125, v125, -2.0, 1.0
	v_fma_f32 v126, v126, -2.0, 1.0
	v_fma_f32 v127, v127, -2.0, 1.0
	v_fma_f32 v128, v128, -2.0, 1.0
	v_add_f32_e32 v121, 1.0, v121
	v_add_f32_e32 v122, 1.0, v122
	v_add_f32_e32 v123, 1.0, v123
	v_add_f32_e32 v124, 1.0, v124
	v_add_f32_e32 v125, 1.0, v125
	v_add_f32_e32 v126, 1.0, v126
	v_add_f32_e32 v127, 1.0, v127
	v_add_f32_e32 v128, 1.0, v128
	v_mul_f32_e32 v121, v129, v121
	v_mul_f32_e32 v122, v130, v122
	v_mul_f32_e32 v123, v131, v123
	v_mul_f32_e32 v124, v132, v124
	v_mul_f32_e32 v125, v133, v125
	v_mul_f32_e32 v126, v134, v126
	v_mul_f32_e32 v127, v135, v127
	v_mul_f32_e32 v128, v138, v128
	v_mul_f32_e32 v48, v48, v121
	v_mul_f32_e32 v49, v49, v122
	v_mul_f32_e32 v50, v50, v123
	v_mul_f32_e32 v51, v51, v124
	v_mul_f32_e32 v52, v52, v125
	v_mul_f32_e32 v53, v53, v126
	v_mul_f32_e32 v54, v54, v127
	v_mul_f32_e32 v55, v55, v128
	v_cvt_pk_bf16_f32 v140, v48, v49
	v_cvt_pk_bf16_f32 v141, v50, v51
	global_store_dwordx2 v[66:67], v[140:141], off
	v_cvt_pk_bf16_f32 v142, v52, v53
	v_cvt_pk_bf16_f32 v143, v54, v55
	global_store_dwordx2 v[66:67], v[142:143], off offset:16
	s_waitcnt vmcnt(14)
; __device__ __forceinline__ unsigned pk2(float lo, float hi) { return f2bf(lo) | (f2bf(hi) << 16); }
; __device__ __forceinline__ float gelu_tanh(float x) {
;     const float u = 0.7978845608028654f * (x + 0.044715f * x * x * x);
;     const float e = __expf(2.0f * u);
;     const float th = 1.0f - 2.0f * __builtin_amdgcn_rcpf(e + 1.0f);
;     return 0.5f * x * (1.0f + th);
; }
; __device__ __forceinline__ void gmlp_fast(KArgs ap, int l, LAS unsigned char* lds, const Ctx cx) {
;     ...
;             for (int ht = 0; ht < 4; ++ht)
; #pragma unroll
;                 for (int q4 = 0; q4 < 4; ++q4) { const u32x2 uu = *(const u32x2*)(zu + ht * 32 + 8 * q4);
;                     const float o0 = gelu_tanh(bflo(uu.x)) * (acc[ht][4 * q4] + bsv), o1 = gelu_tanh(bfhi(uu.x)) * (acc[ht][4 * q4 + 1] + bsv);
;                     const float o2 = gelu_tanh(bflo(uu.y)) * (acc[ht][4 * q4 + 2] + bsv), o3 = gelu_tanh(bfhi(uu.y)) * (acc[ht][4 * q4 + 3] + bsv);
;                     u32x2 w; w.x = pk2(o0, o1); w.y = pk2(o2, o3); *(u32x2*)(yo + ht * 32 + 8 * q4) = w; }
	v_lshlrev_b32_e32 v113, 16, v202
	v_and_b32_e32 v114, 0xffff0000, v202
	v_lshlrev_b32_e32 v115, 16, v203
	v_and_b32_e32 v116, 0xffff0000, v203
	v_lshlrev_b32_e32 v117, 16, v204
	v_and_b32_e32 v118, 0xffff0000, v204
	v_lshlrev_b32_e32 v119, 16, v205
	v_and_b32_e32 v120, 0xffff0000, v205
	v_mul_f32_e32 v121, 0x3d372713, v113
	v_mul_f32_e32 v122, 0x3d372713, v114
	v_mul_f32_e32 v123, 0x3d372713, v115
	v_mul_f32_e32 v124, 0x3d372713, v116
	v_mul_f32_e32 v125, 0x3d372713, v117
	v_mul_f32_e32 v126, 0x3d372713, v118
	v_mul_f32_e32 v127, 0x3d372713, v119
	v_mul_f32_e32 v128, 0x3d372713, v120
	v_mul_f32_e32 v121, v121, v113
	v_mul_f32_e32 v122, v122, v114
	v_mul_f32_e32 v123, v123, v115
	v_mul_f32_e32 v124, v124, v116
	v_mul_f32_e32 v125, v125, v117
	v_mul_f32_e32 v126, v126, v118
	v_mul_f32_e32 v127, v127, v119
	v_mul_f32_e32 v128, v128, v120
	v_fma_f32 v121, v121, v113, v113
	v_fma_f32 v122, v122, v114, v114
	v_fma_f32 v123, v123, v115, v115
	v_fma_f32 v124, v124, v116, v116
	v_fma_f32 v125, v125, v117, v117
	v_fma_f32 v126, v126, v118, v118
	v_fma_f32 v127, v127, v119, v119
	v_fma_f32 v128, v128, v120, v120
	v_mul_f32_e32 v121, 0x3f4c422a, v121
	v_mul_f32_e32 v122, 0x3f4c422a, v122
	v_mul_f32_e32 v123, 0x3f4c422a, v123
	v_mul_f32_e32 v124, 0x3f4c422a, v124
	v_mul_f32_e32 v125, 0x3f4c422a, v125
	v_mul_f32_e32 v126, 0x3f4c422a, v126
	v_mul_f32_e32 v127, 0x3f4c422a, v127
	v_mul_f32_e32 v128, 0x3f4c422a, v128
	v_add_f32_e32 v121, v121, v121
	v_add_f32_e32 v122, v122, v122
	v_add_f32_e32 v123, v123, v123
	v_add_f32_e32 v124, v124, v124
	v_add_f32_e32 v125, v125, v125
	v_add_f32_e32 v126, v126, v126
	v_add_f32_e32 v127, v127, v127
	v_add_f32_e32 v128, v128, v128
	v_mul_f32_e32 v121, 0x3fb8aa3b, v121
	v_mul_f32_e32 v122, 0x3fb8aa3b, v122
	v_mul_f32_e32 v123, 0x3fb8aa3b, v123
	v_mul_f32_e32 v124, 0x3fb8aa3b, v124
	v_mul_f32_e32 v125, 0x3fb8aa3b, v125
	v_mul_f32_e32 v126, 0x3fb8aa3b, v126
	v_mul_f32_e32 v127, 0x3fb8aa3b, v127
	v_mul_f32_e32 v128, 0x3fb8aa3b, v128
	v_exp_f32_e32 v121, v121
	v_exp_f32_e32 v122, v122
	v_exp_f32_e32 v123, v123
	v_exp_f32_e32 v124, v124
	v_exp_f32_e32 v125, v125
	v_exp_f32_e32 v126, v126
	v_exp_f32_e32 v127, v127
	v_exp_f32_e32 v128, v128
	v_mul_f32_e32 v129, 0.5, v113
	v_mul_f32_e32 v130, 0.5, v114
	v_mul_f32_e32 v131, 0.5, v115
	v_mul_f32_e32 v132, 0.5, v116
	v_mul_f32_e32 v133, 0.5, v117
	v_mul_f32_e32 v134, 0.5, v118
	v_mul_f32_e32 v135, 0.5, v119
	v_mul_f32_e32 v138, 0.5, v120
	v_add_f32_e32 v121, 1.0, v121
	v_add_f32_e32 v122, 1.0, v122
	v_add_f32_e32 v123, 1.0, v123
	v_add_f32_e32 v124, 1.0, v124
	v_add_f32_e32 v125, 1.0, v125
	v_add_f32_e32 v126, 1.0, v126
	v_add_f32_e32 v127, 1.0, v127
	v_add_f32_e32 v128, 1.0, v128
	v_rcp_f32_e32 v121, v121
	v_rcp_f32_e32 v122, v122
	v_rcp_f32_e32 v123, v123
	v_rcp_f32_e32 v124, v124
	v_rcp_f32_e32 v125, v125
	v_rcp_f32_e32 v126, v126
	v_rcp_f32_e32 v127, v127
	v_rcp_f32_e32 v128, v128
	v_add_f32_e32 v56, v56, v64
	v_add_f32_e32 v57, v57, v64
	v_add_f32_e32 v58, v58, v64
	v_add_f32_e32 v59, v59, v64
	v_add_f32_e32 v60, v60, v64
	v_add_f32_e32 v61, v61, v64
	v_add_f32_e32 v62, v62, v64
	v_add_f32_e32 v63, v63, v64
	v_fma_f32 v121, v121, -2.0, 1.0
	v_fma_f32 v122, v122, -2.0, 1.0
	v_fma_f32 v123, v123, -2.0, 1.0
	v_fma_f32 v124, v124, -2.0, 1.0
	v_fma_f32 v125, v125, -2.0, 1.0
	v_fma_f32 v126, v126, -2.0, 1.0
	v_fma_f32 v127, v127, -2.0, 1.0
	v_fma_f32 v128, v128, -2.0, 1.0
	v_add_f32_e32 v121, 1.0, v121
	v_add_f32_e32 v122, 1.0, v122
	v_add_f32_e32 v123, 1.0, v123
	v_add_f32_e32 v124, 1.0, v124
	v_add_f32_e32 v125, 1.0, v125
	v_add_f32_e32 v126, 1.0, v126
	v_add_f32_e32 v127, 1.0, v127
	v_add_f32_e32 v128, 1.0, v128
	v_mul_f32_e32 v121, v129, v121
	v_mul_f32_e32 v122, v130, v122
	v_mul_f32_e32 v123, v131, v123
	v_mul_f32_e32 v124, v132, v124
	v_mul_f32_e32 v125, v133, v125
	v_mul_f32_e32 v126, v134, v126
	v_mul_f32_e32 v127, v135, v127
	v_mul_f32_e32 v128, v138, v128
	v_mul_f32_e32 v56, v56, v121
	v_mul_f32_e32 v57, v57, v122
	v_mul_f32_e32 v58, v58, v123
	v_mul_f32_e32 v59, v59, v124
	v_mul_f32_e32 v60, v60, v125
	v_mul_f32_e32 v61, v61, v126
	v_mul_f32_e32 v62, v62, v127
	v_mul_f32_e32 v63, v63, v128
	v_cvt_pk_bf16_f32 v144, v56, v57
	v_cvt_pk_bf16_f32 v145, v58, v59
	global_store_dwordx2 v[66:67], v[144:145], off offset:32
	v_cvt_pk_bf16_f32 v146, v60, v61
	v_cvt_pk_bf16_f32 v147, v62, v63
	global_store_dwordx2 v[66:67], v[146:147], off offset:48
	s_waitcnt vmcnt(14)
; __device__ __forceinline__ unsigned pk2(float lo, float hi) { return f2bf(lo) | (f2bf(hi) << 16); }
; __device__ __forceinline__ float gelu_tanh(float x) {
;     const float u = 0.7978845608028654f * (x + 0.044715f * x * x * x);
;     const float e = __expf(2.0f * u);
;     const float th = 1.0f - 2.0f * __builtin_amdgcn_rcpf(e + 1.0f);
;     return 0.5f * x * (1.0f + th);
; }
; __device__ __forceinline__ void gmlp_fast(KArgs ap, int l, LAS unsigned char* lds, const Ctx cx) {
;     ...
;             for (int ht = 0; ht < 4; ++ht)
; #pragma unroll
;                 for (int q4 = 0; q4 < 4; ++q4) { const u32x2 uu = *(const u32x2*)(zu + ht * 32 + 8 * q4);
;                     const float o0 = gelu_tanh(bflo(uu.x)) * (acc[ht][4 * q4] + bsv), o1 = gelu_tanh(bfhi(uu.x)) * (acc[ht][4 * q4 + 1] + bsv);
;                     const float o2 = gelu_tanh(bflo(uu.y)) * (acc[ht][4 * q4 + 2] + bsv), o3 = gelu_tanh(bfhi(uu.y)) * (acc[ht][4 * q4 + 3] + bsv);
;                     u32x2 w; w.x = pk2(o0, o1); w.y = pk2(o2, o3); *(u32x2*)(yo + ht * 32 + 8 * q4) = w; }
	v_lshlrev_b32_e32 v113, 16, v206
	v_and_b32_e32 v114, 0xffff0000, v206
	v_lshlrev_b32_e32 v115, 16, v207
	v_and_b32_e32 v116, 0xffff0000, v207
	v_lshlrev_b32_e32 v117, 16, v208
	v_and_b32_e32 v118, 0xffff0000, v208
	v_lshlrev_b32_e32 v119, 16, v209
	v_and_b32_e32 v120, 0xffff0000, v209
	v_mul_f32_e32 v121, 0x3d372713, v113
	v_mul_f32_e32 v122, 0x3d372713, v114
	v_mul_f32_e32 v123, 0x3d372713, v115
	v_mul_f32_e32 v124, 0x3d372713, v116
	v_mul_f32_e32 v125, 0x3d372713, v117
	v_mul_f32_e32 v126, 0x3d372713, v118
	v_mul_f32_e32 v127, 0x3d372713, v119
	v_mul_f32_e32 v128, 0x3d372713, v120
	v_mul_f32_e32 v121, v121, v113
	v_mul_f32_e32 v122, v122, v114
	v_mul_f32_e32 v123, v123, v115
	v_mul_f32_e32 v124, v124, v116
	v_mul_f32_e32 v125, v125, v117
	v_mul_f32_e32 v126, v126, v118
	v_mul_f32_e32 v127, v127, v119
	v_mul_f32_e32 v128, v128, v120
	v_fma_f32 v121, v121, v113, v113
	v_fma_f32 v122, v122, v114, v114
	v_fma_f32 v123, v123, v115, v115
	v_fma_f32 v124, v124, v116, v116
	v_fma_f32 v125, v125, v117, v117
	v_fma_f32 v126, v126, v118, v118
	v_fma_f32 v127, v127, v119, v119
	v_fma_f32 v128, v128, v120, v120
	v_mul_f32_e32 v121, 0x3f4c422a, v121
	v_mul_f32_e32 v122, 0x3f4c422a, v122
	v_mul_f32_e32 v123, 0x3f4c422a, v123
	v_mul_f32_e32 v124, 0x3f4c422a, v124
	v_mul_f32_e32 v125, 0x3f4c422a, v125
	v_mul_f32_e32 v126, 0x3f4c422a, v126
	v_mul_f32_e32 v127, 0x3f4c422a, v127
	v_mul_f32_e32 v128, 0x3f4c422a, v128
	v_add_f32_e32 v121, v121, v121
	v_add_f32_e32 v122, v122, v122
	v_add_f32_e32 v123, v123, v123
	v_add_f32_e32 v124, v124, v124
	v_add_f32_e32 v125, v125, v125
	v_add_f32_e32 v126, v126, v126
	v_add_f32_e32 v127, v127, v127
	v_add_f32_e32 v128, v128, v128
	v_mul_f32_e32 v121, 0x3fb8aa3b, v121
	v_mul_f32_e32 v122, 0x3fb8aa3b, v122
	v_mul_f32_e32 v123, 0x3fb8aa3b, v123
	v_mul_f32_e32 v124, 0x3fb8aa3b, v124
	v_mul_f32_e32 v125, 0x3fb8aa3b, v125
	v_mul_f32_e32 v126, 0x3fb8aa3b, v126
	v_mul_f32_e32 v127, 0x3fb8aa3b, v127
	v_mul_f32_e32 v128, 0x3fb8aa3b, v128
	v_exp_f32_e32 v121, v121
	v_exp_f32_e32 v122, v122
	v_exp_f32_e32 v123, v123
	v_exp_f32_e32 v124, v124
	v_exp_f32_e32 v125, v125
	v_exp_f32_e32 v126, v126
	v_exp_f32_e32 v127, v127
	v_exp_f32_e32 v128, v128
	v_mul_f32_e32 v129, 0.5, v113
	v_mul_f32_e32 v130, 0.5, v114
	v_mul_f32_e32 v131, 0.5, v115
	v_mul_f32_e32 v132, 0.5, v116
	v_mul_f32_e32 v133, 0.5, v117
	v_mul_f32_e32 v134, 0.5, v118
	v_mul_f32_e32 v135, 0.5, v119
	v_mul_f32_e32 v138, 0.5, v120
	v_add_f32_e32 v121, 1.0, v121
	v_add_f32_e32 v122, 1.0, v122
	v_add_f32_e32 v123, 1.0, v123
	v_add_f32_e32 v124, 1.0, v124
	v_add_f32_e32 v125, 1.0, v125
	v_add_f32_e32 v126, 1.0, v126
	v_add_f32_e32 v127, 1.0, v127
	v_add_f32_e32 v128, 1.0, v128
	v_rcp_f32_e32 v121, v121
	v_rcp_f32_e32 v122, v122
	v_rcp_f32_e32 v123, v123
	v_rcp_f32_e32 v124, v124
	v_rcp_f32_e32 v125, v125
	v_rcp_f32_e32 v126, v126
	v_rcp_f32_e32 v127, v127
	v_rcp_f32_e32 v128, v128
	v_add_f32_e32 v32, v32, v64
	v_add_f32_e32 v33, v33, v64
	v_add_f32_e32 v34, v34, v64
	v_add_f32_e32 v35, v35, v64
	v_add_f32_e32 v36, v36, v64
	v_add_f32_e32 v37, v37, v64
	v_add_f32_e32 v38, v38, v64
	v_add_f32_e32 v39, v39, v64
	v_fma_f32 v121, v121, -2.0, 1.0
	v_fma_f32 v122, v122, -2.0, 1.0
	v_fma_f32 v123, v123, -2.0, 1.0
	v_fma_f32 v124, v124, -2.0, 1.0
	v_fma_f32 v125, v125, -2.0, 1.0
	v_fma_f32 v126, v126, -2.0, 1.0
	v_fma_f32 v127, v127, -2.0, 1.0
	v_fma_f32 v128, v128, -2.0, 1.0
	v_add_f32_e32 v121, 1.0, v121
	v_add_f32_e32 v122, 1.0, v122
	v_add_f32_e32 v123, 1.0, v123
	v_add_f32_e32 v124, 1.0, v124
	v_add_f32_e32 v125, 1.0, v125
	v_add_f32_e32 v126, 1.0, v126
	v_add_f32_e32 v127, 1.0, v127
	v_add_f32_e32 v128, 1.0, v128
	v_mul_f32_e32 v121, v129, v121
	v_mul_f32_e32 v122, v130, v122
	v_mul_f32_e32 v123, v131, v123
	v_mul_f32_e32 v124, v132, v124
	v_mul_f32_e32 v125, v133, v125
	v_mul_f32_e32 v126, v134, v126
	v_mul_f32_e32 v127, v135, v127
	v_mul_f32_e32 v128, v138, v128
	v_mul_f32_e32 v32, v32, v121
	v_mul_f32_e32 v33, v33, v122
	v_mul_f32_e32 v34, v34, v123
	v_mul_f32_e32 v35, v35, v124
	v_mul_f32_e32 v36, v36, v125
	v_mul_f32_e32 v37, v37, v126
	v_mul_f32_e32 v38, v38, v127
	v_mul_f32_e32 v39, v39, v128
	v_cvt_pk_bf16_f32 v140, v32, v33
	v_cvt_pk_bf16_f32 v141, v34, v35
	global_store_dwordx2 v[66:67], v[140:141], off offset:64
	v_cvt_pk_bf16_f32 v142, v36, v37
	v_cvt_pk_bf16_f32 v143, v38, v39
	global_store_dwordx2 v[66:67], v[142:143], off offset:80
	s_waitcnt vmcnt(14)
; __device__ __forceinline__ unsigned pk2(float lo, float hi) { return f2bf(lo) | (f2bf(hi) << 16); }
; __device__ __forceinline__ float gelu_tanh(float x) {
;     const float u = 0.7978845608028654f * (x + 0.044715f * x * x * x);
;     const float e = __expf(2.0f * u);
;     const float th = 1.0f - 2.0f * __builtin_amdgcn_rcpf(e + 1.0f);
;     return 0.5f * x * (1.0f + th);
; }
; __device__ __forceinline__ void gmlp_fast(KArgs ap, int l, LAS unsigned char* lds, const Ctx cx) {
;     ...
;             for (int ht = 0; ht < 4; ++ht)
; #pragma unroll
;                 for (int q4 = 0; q4 < 4; ++q4) { const u32x2 uu = *(const u32x2*)(zu + ht * 32 + 8 * q4);
;                     const float o0 = gelu_tanh(bflo(uu.x)) * (acc[ht][4 * q4] + bsv), o1 = gelu_tanh(bfhi(uu.x)) * (acc[ht][4 * q4 + 1] + bsv);
;                     const float o2 = gelu_tanh(bflo(uu.y)) * (acc[ht][4 * q4 + 2] + bsv), o3 = gelu_tanh(bfhi(uu.y)) * (acc[ht][4 * q4 + 3] + bsv);
;                     u32x2 w; w.x = pk2(o0, o1); w.y = pk2(o2, o3); *(u32x2*)(yo + ht * 32 + 8 * q4) = w; }
	v_lshlrev_b32_e32 v113, 16, v210
	v_and_b32_e32 v114, 0xffff0000, v210
	v_lshlrev_b32_e32 v115, 16, v211
	v_and_b32_e32 v116, 0xffff0000, v211
	v_lshlrev_b32_e32 v117, 16, v212
	v_and_b32_e32 v118, 0xffff0000, v212
	v_lshlrev_b32_e32 v119, 16, v213
	v_and_b32_e32 v120, 0xffff0000, v213
	v_mul_f32_e32 v121, 0x3d372713, v113
	v_mul_f32_e32 v122, 0x3d372713, v114
	v_mul_f32_e32 v123, 0x3d372713, v115
	v_mul_f32_e32 v124, 0x3d372713, v116
	v_mul_f32_e32 v125, 0x3d372713, v117
	v_mul_f32_e32 v126, 0x3d372713, v118
	v_mul_f32_e32 v127, 0x3d372713, v119
	v_mul_f32_e32 v128, 0x3d372713, v120
	v_mul_f32_e32 v121, v121, v113
	v_mul_f32_e32 v122, v122, v114
	v_mul_f32_e32 v123, v123, v115
	v_mul_f32_e32 v124, v124, v116
	v_mul_f32_e32 v125, v125, v117
	v_mul_f32_e32 v126, v126, v118
	v_mul_f32_e32 v127, v127, v119
	v_mul_f32_e32 v128, v128, v120
	v_fma_f32 v121, v121, v113, v113
	v_fma_f32 v122, v122, v114, v114
	v_fma_f32 v123, v123, v115, v115
	v_fma_f32 v124, v124, v116, v116
	v_fma_f32 v125, v125, v117, v117
	v_fma_f32 v126, v126, v118, v118
	v_fma_f32 v127, v127, v119, v119
	v_fma_f32 v128, v128, v120, v120
	v_mul_f32_e32 v121, 0x3f4c422a, v121
	v_mul_f32_e32 v122, 0x3f4c422a, v122
	v_mul_f32_e32 v123, 0x3f4c422a, v123
	v_mul_f32_e32 v124, 0x3f4c422a, v124
	v_mul_f32_e32 v125, 0x3f4c422a, v125
	v_mul_f32_e32 v126, 0x3f4c422a, v126
	v_mul_f32_e32 v127, 0x3f4c422a, v127
	v_mul_f32_e32 v128, 0x3f4c422a, v128
	v_add_f32_e32 v121, v121, v121
	v_add_f32_e32 v122, v122, v122
	v_add_f32_e32 v123, v123, v123
	v_add_f32_e32 v124, v124, v124
	v_add_f32_e32 v125, v125, v125
	v_add_f32_e32 v126, v126, v126
	v_add_f32_e32 v127, v127, v127
	v_add_f32_e32 v128, v128, v128
	v_mul_f32_e32 v121, 0x3fb8aa3b, v121
	v_mul_f32_e32 v122, 0x3fb8aa3b, v122
	v_mul_f32_e32 v123, 0x3fb8aa3b, v123
	v_mul_f32_e32 v124, 0x3fb8aa3b, v124
	v_mul_f32_e32 v125, 0x3fb8aa3b, v125
	v_mul_f32_e32 v126, 0x3fb8aa3b, v126
	v_mul_f32_e32 v127, 0x3fb8aa3b, v127
	v_mul_f32_e32 v128, 0x3fb8aa3b, v128
	v_exp_f32_e32 v121, v121
	v_exp_f32_e32 v122, v122
	v_exp_f32_e32 v123, v123
	v_exp_f32_e32 v124, v124
	v_exp_f32_e32 v125, v125
	v_exp_f32_e32 v126, v126
	v_exp_f32_e32 v127, v127
	v_exp_f32_e32 v128, v128
	v_mul_f32_e32 v129, 0.5, v113
	v_mul_f32_e32 v130, 0.5, v114
	v_mul_f32_e32 v131, 0.5, v115
	v_mul_f32_e32 v132, 0.5, v116
	v_mul_f32_e32 v133, 0.5, v117
	v_mul_f32_e32 v134, 0.5, v118
	v_mul_f32_e32 v135, 0.5, v119
	v_mul_f32_e32 v138, 0.5, v120
	v_add_f32_e32 v121, 1.0, v121
	v_add_f32_e32 v122, 1.0, v122
	v_add_f32_e32 v123, 1.0, v123
	v_add_f32_e32 v124, 1.0, v124
	v_add_f32_e32 v125, 1.0, v125
	v_add_f32_e32 v126, 1.0, v126
	v_add_f32_e32 v127, 1.0, v127
	v_add_f32_e32 v128, 1.0, v128
	v_rcp_f32_e32 v121, v121
	v_rcp_f32_e32 v122, v122
	v_rcp_f32_e32 v123, v123
	v_rcp_f32_e32 v124, v124
	v_rcp_f32_e32 v125, v125
	v_rcp_f32_e32 v126, v126
	v_rcp_f32_e32 v127, v127
	v_rcp_f32_e32 v128, v128
	v_add_f32_e32 v40, v40, v64
	v_add_f32_e32 v41, v41, v64
	v_add_f32_e32 v42, v42, v64
	v_add_f32_e32 v43, v43, v64
	v_add_f32_e32 v44, v44, v64
	v_add_f32_e32 v45, v45, v64
	v_add_f32_e32 v46, v46, v64
	v_add_f32_e32 v47, v47, v64
	v_fma_f32 v121, v121, -2.0, 1.0
	v_fma_f32 v122, v122, -2.0, 1.0
	v_fma_f32 v123, v123, -2.0, 1.0
	v_fma_f32 v124, v124, -2.0, 1.0
	v_fma_f32 v125, v125, -2.0, 1.0
	v_fma_f32 v126, v126, -2.0, 1.0
	v_fma_f32 v127, v127, -2.0, 1.0
	v_fma_f32 v128, v128, -2.0, 1.0
	v_add_f32_e32 v121, 1.0, v121
	v_add_f32_e32 v122, 1.0, v122
	v_add_f32_e32 v123, 1.0, v123
	v_add_f32_e32 v124, 1.0, v124
	v_add_f32_e32 v125, 1.0, v125
	v_add_f32_e32 v126, 1.0, v126
	v_add_f32_e32 v127, 1.0, v127
	v_add_f32_e32 v128, 1.0, v128
	v_mul_f32_e32 v121, v129, v121
	v_mul_f32_e32 v122, v130, v122
	v_mul_f32_e32 v123, v131, v123
	v_mul_f32_e32 v124, v132, v124
	v_mul_f32_e32 v125, v133, v125
	v_mul_f32_e32 v126, v134, v126
	v_mul_f32_e32 v127, v135, v127
	v_mul_f32_e32 v128, v138, v128
	v_mul_f32_e32 v40, v40, v121
	v_mul_f32_e32 v41, v41, v122
	v_mul_f32_e32 v42, v42, v123
	v_mul_f32_e32 v43, v43, v124
	v_mul_f32_e32 v44, v44, v125
	v_mul_f32_e32 v45, v45, v126
	v_mul_f32_e32 v46, v46, v127
	v_mul_f32_e32 v47, v47, v128
	v_cvt_pk_bf16_f32 v144, v40, v41
	v_cvt_pk_bf16_f32 v145, v42, v43
	global_store_dwordx2 v[66:67], v[144:145], off offset:96
	v_cvt_pk_bf16_f32 v146, v44, v45
	v_cvt_pk_bf16_f32 v147, v46, v47
	global_store_dwordx2 v[66:67], v[146:147], off offset:112
	s_waitcnt vmcnt(14)
; __device__ __forceinline__ unsigned pk2(float lo, float hi) { return f2bf(lo) | (f2bf(hi) << 16); }
; __device__ __forceinline__ float gelu_tanh(float x) {
;     const float u = 0.7978845608028654f * (x + 0.044715f * x * x * x);
;     const float e = __expf(2.0f * u);
;     const float th = 1.0f - 2.0f * __builtin_amdgcn_rcpf(e + 1.0f);
;     return 0.5f * x * (1.0f + th);
; }
; __device__ __forceinline__ void gmlp_fast(KArgs ap, int l, LAS unsigned char* lds, const Ctx cx) {
;     ...
;             for (int ht = 0; ht < 4; ++ht)
; #pragma unroll
;                 for (int q4 = 0; q4 < 4; ++q4) { const u32x2 uu = *(const u32x2*)(zu + ht * 32 + 8 * q4);
;                     const float o0 = gelu_tanh(bflo(uu.x)) * (acc[ht][4 * q4] + bsv), o1 = gelu_tanh(bfhi(uu.x)) * (acc[ht][4 * q4 + 1] + bsv);
;                     const float o2 = gelu_tanh(bflo(uu.y)) * (acc[ht][4 * q4 + 2] + bsv), o3 = gelu_tanh(bfhi(uu.y)) * (acc[ht][4 * q4 + 3] + bsv);
;                     u32x2 w; w.x = pk2(o0, o1); w.y = pk2(o2, o3); *(u32x2*)(yo + ht * 32 + 8 * q4) = w; }
	v_lshlrev_b32_e32 v113, 16, v214
	v_and_b32_e32 v114, 0xffff0000, v214
	v_lshlrev_b32_e32 v115, 16, v215
	v_and_b32_e32 v116, 0xffff0000, v215
	v_lshlrev_b32_e32 v117, 16, v216
	v_and_b32_e32 v118, 0xffff0000, v216
	v_lshlrev_b32_e32 v119, 16, v217
	v_and_b32_e32 v120, 0xffff0000, v217
	v_mul_f32_e32 v121, 0x3d372713, v113
	v_mul_f32_e32 v122, 0x3d372713, v114
	v_mul_f32_e32 v123, 0x3d372713, v115
	v_mul_f32_e32 v124, 0x3d372713, v116
	v_mul_f32_e32 v125, 0x3d372713, v117
	v_mul_f32_e32 v126, 0x3d372713, v118
	v_mul_f32_e32 v127, 0x3d372713, v119
	v_mul_f32_e32 v128, 0x3d372713, v120
	v_mul_f32_e32 v121, v121, v113
	v_mul_f32_e32 v122, v122, v114
	v_mul_f32_e32 v123, v123, v115
	v_mul_f32_e32 v124, v124, v116
	v_mul_f32_e32 v125, v125, v117
	v_mul_f32_e32 v126, v126, v118
	v_mul_f32_e32 v127, v127, v119
	v_mul_f32_e32 v128, v128, v120
	v_fma_f32 v121, v121, v113, v113
	v_fma_f32 v122, v122, v114, v114
	v_fma_f32 v123, v123, v115, v115
	v_fma_f32 v124, v124, v116, v116
	v_fma_f32 v125, v125, v117, v117
	v_fma_f32 v126, v126, v118, v118
	v_fma_f32 v127, v127, v119, v119
	v_fma_f32 v128, v128, v120, v120
	v_mul_f32_e32 v121, 0x3f4c422a, v121
	v_mul_f32_e32 v122, 0x3f4c422a, v122
	v_mul_f32_e32 v123, 0x3f4c422a, v123
	v_mul_f32_e32 v124, 0x3f4c422a, v124
	v_mul_f32_e32 v125, 0x3f4c422a, v125
	v_mul_f32_e32 v126, 0x3f4c422a, v126
	v_mul_f32_e32 v127, 0x3f4c422a, v127
	v_mul_f32_e32 v128, 0x3f4c422a, v128
	v_add_f32_e32 v121, v121, v121
	v_add_f32_e32 v122, v122, v122
	v_add_f32_e32 v123, v123, v123
	v_add_f32_e32 v124, v124, v124
	v_add_f32_e32 v125, v125, v125
	v_add_f32_e32 v126, v126, v126
	v_add_f32_e32 v127, v127, v127
	v_add_f32_e32 v128, v128, v128
	v_mul_f32_e32 v121, 0x3fb8aa3b, v121
	v_mul_f32_e32 v122, 0x3fb8aa3b, v122
	v_mul_f32_e32 v123, 0x3fb8aa3b, v123
	v_mul_f32_e32 v124, 0x3fb8aa3b, v124
	v_mul_f32_e32 v125, 0x3fb8aa3b, v125
	v_mul_f32_e32 v126, 0x3fb8aa3b, v126
	v_mul_f32_e32 v127, 0x3fb8aa3b, v127
	v_mul_f32_e32 v128, 0x3fb8aa3b, v128
	v_exp_f32_e32 v121, v121
	v_exp_f32_e32 v122, v122
	v_exp_f32_e32 v123, v123
	v_exp_f32_e32 v124, v124
	v_exp_f32_e32 v125, v125
	v_exp_f32_e32 v126, v126
	v_exp_f32_e32 v127, v127
	v_exp_f32_e32 v128, v128
	v_mul_f32_e32 v129, 0.5, v113
	v_mul_f32_e32 v130, 0.5, v114
	v_mul_f32_e32 v131, 0.5, v115
	v_mul_f32_e32 v132, 0.5, v116
	v_mul_f32_e32 v133, 0.5, v117
	v_mul_f32_e32 v134, 0.5, v118
	v_mul_f32_e32 v135, 0.5, v119
	v_mul_f32_e32 v138, 0.5, v120
	v_add_f32_e32 v121, 1.0, v121
	v_add_f32_e32 v122, 1.0, v122
	v_add_f32_e32 v123, 1.0, v123
	v_add_f32_e32 v124, 1.0, v124
	v_add_f32_e32 v125, 1.0, v125
	v_add_f32_e32 v126, 1.0, v126
	v_add_f32_e32 v127, 1.0, v127
	v_add_f32_e32 v128, 1.0, v128
	v_rcp_f32_e32 v121, v121
	v_rcp_f32_e32 v122, v122
	v_rcp_f32_e32 v123, v123
	v_rcp_f32_e32 v124, v124
	v_rcp_f32_e32 v125, v125
	v_rcp_f32_e32 v126, v126
	v_rcp_f32_e32 v127, v127
	v_rcp_f32_e32 v128, v128
	v_add_f32_e32 v16, v16, v64
	v_add_f32_e32 v17, v17, v64
	v_add_f32_e32 v18, v18, v64
	v_add_f32_e32 v19, v19, v64
	v_add_f32_e32 v20, v20, v64
	v_add_f32_e32 v21, v21, v64
	v_add_f32_e32 v22, v22, v64
	v_add_f32_e32 v23, v23, v64
	v_fma_f32 v121, v121, -2.0, 1.0
	v_fma_f32 v122, v122, -2.0, 1.0
	v_fma_f32 v123, v123, -2.0, 1.0
	v_fma_f32 v124, v124, -2.0, 1.0
	v_fma_f32 v125, v125, -2.0, 1.0
	v_fma_f32 v126, v126, -2.0, 1.0
	v_fma_f32 v127, v127, -2.0, 1.0
	v_fma_f32 v128, v128, -2.0, 1.0
	v_add_f32_e32 v121, 1.0, v121
	v_add_f32_e32 v122, 1.0, v122
	v_add_f32_e32 v123, 1.0, v123
	v_add_f32_e32 v124, 1.0, v124
	v_add_f32_e32 v125, 1.0, v125
	v_add_f32_e32 v126, 1.0, v126
	v_add_f32_e32 v127, 1.0, v127
	v_add_f32_e32 v128, 1.0, v128
	v_mul_f32_e32 v121, v129, v121
	v_mul_f32_e32 v122, v130, v122
	v_mul_f32_e32 v123, v131, v123
	v_mul_f32_e32 v124, v132, v124
	v_mul_f32_e32 v125, v133, v125
	v_mul_f32_e32 v126, v134, v126
	v_mul_f32_e32 v127, v135, v127
	v_mul_f32_e32 v128, v138, v128
	v_mul_f32_e32 v16, v16, v121
	v_mul_f32_e32 v17, v17, v122
	v_mul_f32_e32 v18, v18, v123
	v_mul_f32_e32 v19, v19, v124
	v_mul_f32_e32 v20, v20, v125
	v_mul_f32_e32 v21, v21, v126
	v_mul_f32_e32 v22, v22, v127
	v_mul_f32_e32 v23, v23, v128
	v_cvt_pk_bf16_f32 v140, v16, v17
	v_cvt_pk_bf16_f32 v141, v18, v19
	global_store_dwordx2 v[66:67], v[140:141], off offset:128
	v_cvt_pk_bf16_f32 v142, v20, v21
	v_cvt_pk_bf16_f32 v143, v22, v23
	global_store_dwordx2 v[66:67], v[142:143], off offset:144
	s_waitcnt vmcnt(14)
; __device__ __forceinline__ unsigned pk2(float lo, float hi) { return f2bf(lo) | (f2bf(hi) << 16); }
; __device__ __forceinline__ float gelu_tanh(float x) {
;     const float u = 0.7978845608028654f * (x + 0.044715f * x * x * x);
;     const float e = __expf(2.0f * u);
;     const float th = 1.0f - 2.0f * __builtin_amdgcn_rcpf(e + 1.0f);
;     return 0.5f * x * (1.0f + th);
; }
; __device__ __forceinline__ void gmlp_fast(KArgs ap, int l, LAS unsigned char* lds, const Ctx cx) {
;     ...
;             for (int ht = 0; ht < 4; ++ht)
; #pragma unroll
;                 for (int q4 = 0; q4 < 4; ++q4) { const u32x2 uu = *(const u32x2*)(zu + ht * 32 + 8 * q4);
;                     const float o0 = gelu_tanh(bflo(uu.x)) * (acc[ht][4 * q4] + bsv), o1 = gelu_tanh(bfhi(uu.x)) * (acc[ht][4 * q4 + 1] + bsv);
;                     const float o2 = gelu_tanh(bflo(uu.y)) * (acc[ht][4 * q4 + 2] + bsv), o3 = gelu_tanh(bfhi(uu.y)) * (acc[ht][4 * q4 + 3] + bsv);
;                     u32x2 w; w.x = pk2(o0, o1); w.y = pk2(o2, o3); *(u32x2*)(yo + ht * 32 + 8 * q4) = w; }
	v_lshlrev_b32_e32 v113, 16, v218
	v_and_b32_e32 v114, 0xffff0000, v218
	v_lshlrev_b32_e32 v115, 16, v219
	v_and_b32_e32 v116, 0xffff0000, v219
	v_lshlrev_b32_e32 v117, 16, v220
	v_and_b32_e32 v118, 0xffff0000, v220
	v_lshlrev_b32_e32 v119, 16, v221
	v_and_b32_e32 v120, 0xffff0000, v221
	v_mul_f32_e32 v121, 0x3d372713, v113
	v_mul_f32_e32 v122, 0x3d372713, v114
	v_mul_f32_e32 v123, 0x3d372713, v115
	v_mul_f32_e32 v124, 0x3d372713, v116
	v_mul_f32_e32 v125, 0x3d372713, v117
	v_mul_f32_e32 v126, 0x3d372713, v118
	v_mul_f32_e32 v127, 0x3d372713, v119
	v_mul_f32_e32 v128, 0x3d372713, v120
	v_mul_f32_e32 v121, v121, v113
	v_mul_f32_e32 v122, v122, v114
	v_mul_f32_e32 v123, v123, v115
	v_mul_f32_e32 v124, v124, v116
	v_mul_f32_e32 v125, v125, v117
	v_mul_f32_e32 v126, v126, v118
	v_mul_f32_e32 v127, v127, v119
	v_mul_f32_e32 v128, v128, v120
	v_fma_f32 v121, v121, v113, v113
	v_fma_f32 v122, v122, v114, v114
	v_fma_f32 v123, v123, v115, v115
	v_fma_f32 v124, v124, v116, v116
	v_fma_f32 v125, v125, v117, v117
	v_fma_f32 v126, v126, v118, v118
	v_fma_f32 v127, v127, v119, v119
	v_fma_f32 v128, v128, v120, v120
	v_mul_f32_e32 v121, 0x3f4c422a, v121
	v_mul_f32_e32 v122, 0x3f4c422a, v122
	v_mul_f32_e32 v123, 0x3f4c422a, v123
	v_mul_f32_e32 v124, 0x3f4c422a, v124
	v_mul_f32_e32 v125, 0x3f4c422a, v125
	v_mul_f32_e32 v126, 0x3f4c422a, v126
	v_mul_f32_e32 v127, 0x3f4c422a, v127
	v_mul_f32_e32 v128, 0x3f4c422a, v128
	v_add_f32_e32 v121, v121, v121
	v_add_f32_e32 v122, v122, v122
	v_add_f32_e32 v123, v123, v123
	v_add_f32_e32 v124, v124, v124
	v_add_f32_e32 v125, v125, v125
	v_add_f32_e32 v126, v126, v126
	v_add_f32_e32 v127, v127, v127
	v_add_f32_e32 v128, v128, v128
	v_mul_f32_e32 v121, 0x3fb8aa3b, v121
	v_mul_f32_e32 v122, 0x3fb8aa3b, v122
	v_mul_f32_e32 v123, 0x3fb8aa3b, v123
	v_mul_f32_e32 v124, 0x3fb8aa3b, v124
	v_mul_f32_e32 v125, 0x3fb8aa3b, v125
	v_mul_f32_e32 v126, 0x3fb8aa3b, v126
	v_mul_f32_e32 v127, 0x3fb8aa3b, v127
	v_mul_f32_e32 v128, 0x3fb8aa3b, v128
	v_exp_f32_e32 v121, v121
	v_exp_f32_e32 v122, v122
	v_exp_f32_e32 v123, v123
	v_exp_f32_e32 v124, v124
	v_exp_f32_e32 v125, v125
	v_exp_f32_e32 v126, v126
	v_exp_f32_e32 v127, v127
	v_exp_f32_e32 v128, v128
	v_mul_f32_e32 v129, 0.5, v113
	v_mul_f32_e32 v130, 0.5, v114
	v_mul_f32_e32 v131, 0.5, v115
	v_mul_f32_e32 v132, 0.5, v116
	v_mul_f32_e32 v133, 0.5, v117
	v_mul_f32_e32 v134, 0.5, v118
	v_mul_f32_e32 v135, 0.5, v119
	v_mul_f32_e32 v138, 0.5, v120
	v_add_f32_e32 v121, 1.0, v121
	v_add_f32_e32 v122, 1.0, v122
	v_add_f32_e32 v123, 1.0, v123
	v_add_f32_e32 v124, 1.0, v124
	v_add_f32_e32 v125, 1.0, v125
	v_add_f32_e32 v126, 1.0, v126
	v_add_f32_e32 v127, 1.0, v127
	v_add_f32_e32 v128, 1.0, v128
	v_rcp_f32_e32 v121, v121
	v_rcp_f32_e32 v122, v122
	v_rcp_f32_e32 v123, v123
	v_rcp_f32_e32 v124, v124
	v_rcp_f32_e32 v125, v125
	v_rcp_f32_e32 v126, v126
	v_rcp_f32_e32 v127, v127
	v_rcp_f32_e32 v128, v128
	v_add_f32_e32 v24, v24, v64
	v_add_f32_e32 v25, v25, v64
	v_add_f32_e32 v26, v26, v64
	v_add_f32_e32 v27, v27, v64
	v_add_f32_e32 v28, v28, v64
	v_add_f32_e32 v29, v29, v64
	v_add_f32_e32 v30, v30, v64
	v_add_f32_e32 v31, v31, v64
	v_fma_f32 v121, v121, -2.0, 1.0
	v_fma_f32 v122, v122, -2.0, 1.0
	v_fma_f32 v123, v123, -2.0, 1.0
	v_fma_f32 v124, v124, -2.0, 1.0
	v_fma_f32 v125, v125, -2.0, 1.0
	v_fma_f32 v126, v126, -2.0, 1.0
	v_fma_f32 v127, v127, -2.0, 1.0
	v_fma_f32 v128, v128, -2.0, 1.0
	v_add_f32_e32 v121, 1.0, v121
	v_add_f32_e32 v122, 1.0, v122
	v_add_f32_e32 v123, 1.0, v123
	v_add_f32_e32 v124, 1.0, v124
	v_add_f32_e32 v125, 1.0, v125
	v_add_f32_e32 v126, 1.0, v126
	v_add_f32_e32 v127, 1.0, v127
	v_add_f32_e32 v128, 1.0, v128
	v_mul_f32_e32 v121, v129, v121
	v_mul_f32_e32 v122, v130, v122
	v_mul_f32_e32 v123, v131, v123
	v_mul_f32_e32 v124, v132, v124
	v_mul_f32_e32 v125, v133, v125
	v_mul_f32_e32 v126, v134, v126
	v_mul_f32_e32 v127, v135, v127
	v_mul_f32_e32 v128, v138, v128
	v_mul_f32_e32 v24, v24, v121
	v_mul_f32_e32 v25, v25, v122
	v_mul_f32_e32 v26, v26, v123
	v_mul_f32_e32 v27, v27, v124
	v_mul_f32_e32 v28, v28, v125
	v_mul_f32_e32 v29, v29, v126
	v_mul_f32_e32 v30, v30, v127
	v_mul_f32_e32 v31, v31, v128
	v_cvt_pk_bf16_f32 v144, v24, v25
	v_cvt_pk_bf16_f32 v145, v26, v27
	global_store_dwordx2 v[66:67], v[144:145], off offset:160
	v_cvt_pk_bf16_f32 v146, v28, v29
	v_cvt_pk_bf16_f32 v147, v30, v31
	global_store_dwordx2 v[66:67], v[146:147], off offset:176
	s_waitcnt vmcnt(14)
; __device__ __forceinline__ unsigned pk2(float lo, float hi) { return f2bf(lo) | (f2bf(hi) << 16); }
; __device__ __forceinline__ float gelu_tanh(float x) {
;     const float u = 0.7978845608028654f * (x + 0.044715f * x * x * x);
;     const float e = __expf(2.0f * u);
;     const float th = 1.0f - 2.0f * __builtin_amdgcn_rcpf(e + 1.0f);
;     return 0.5f * x * (1.0f + th);
; }
; __device__ __forceinline__ void gmlp_fast(KArgs ap, int l, LAS unsigned char* lds, const Ctx cx) {
;     ...
;             for (int ht = 0; ht < 4; ++ht)
; #pragma unroll
;                 for (int q4 = 0; q4 < 4; ++q4) { const u32x2 uu = *(const u32x2*)(zu + ht * 32 + 8 * q4);
;                     const float o0 = gelu_tanh(bflo(uu.x)) * (acc[ht][4 * q4] + bsv), o1 = gelu_tanh(bfhi(uu.x)) * (acc[ht][4 * q4 + 1] + bsv);
;                     const float o2 = gelu_tanh(bflo(uu.y)) * (acc[ht][4 * q4 + 2] + bsv), o3 = gelu_tanh(bfhi(uu.y)) * (acc[ht][4 * q4 + 3] + bsv);
;                     u32x2 w; w.x = pk2(o0, o1); w.y = pk2(o2, o3); *(u32x2*)(yo + ht * 32 + 8 * q4) = w; }
	v_lshlrev_b32_e32 v113, 16, v222
	v_and_b32_e32 v114, 0xffff0000, v222
	v_lshlrev_b32_e32 v115, 16, v223
	v_and_b32_e32 v116, 0xffff0000, v223
	v_lshlrev_b32_e32 v117, 16, v224
	v_and_b32_e32 v118, 0xffff0000, v224
	v_lshlrev_b32_e32 v119, 16, v225
	v_and_b32_e32 v120, 0xffff0000, v225
	v_mul_f32_e32 v121, 0x3d372713, v113
	v_mul_f32_e32 v122, 0x3d372713, v114
	v_mul_f32_e32 v123, 0x3d372713, v115
	v_mul_f32_e32 v124, 0x3d372713, v116
	v_mul_f32_e32 v125, 0x3d372713, v117
	v_mul_f32_e32 v126, 0x3d372713, v118
	v_mul_f32_e32 v127, 0x3d372713, v119
	v_mul_f32_e32 v128, 0x3d372713, v120
	v_mul_f32_e32 v121, v121, v113
	v_mul_f32_e32 v122, v122, v114
	v_mul_f32_e32 v123, v123, v115
	v_mul_f32_e32 v124, v124, v116
	v_mul_f32_e32 v125, v125, v117
	v_mul_f32_e32 v126, v126, v118
	v_mul_f32_e32 v127, v127, v119
	v_mul_f32_e32 v128, v128, v120
	v_fma_f32 v121, v121, v113, v113
	v_fma_f32 v122, v122, v114, v114
	v_fma_f32 v123, v123, v115, v115
	v_fma_f32 v124, v124, v116, v116
	v_fma_f32 v125, v125, v117, v117
	v_fma_f32 v126, v126, v118, v118
	v_fma_f32 v127, v127, v119, v119
	v_fma_f32 v128, v128, v120, v120
	v_mul_f32_e32 v121, 0x3f4c422a, v121
	v_mul_f32_e32 v122, 0x3f4c422a, v122
	v_mul_f32_e32 v123, 0x3f4c422a, v123
	v_mul_f32_e32 v124, 0x3f4c422a, v124
	v_mul_f32_e32 v125, 0x3f4c422a, v125
	v_mul_f32_e32 v126, 0x3f4c422a, v126
	v_mul_f32_e32 v127, 0x3f4c422a, v127
	v_mul_f32_e32 v128, 0x3f4c422a, v128
	v_add_f32_e32 v121, v121, v121
	v_add_f32_e32 v122, v122, v122
	v_add_f32_e32 v123, v123, v123
	v_add_f32_e32 v124, v124, v124
	v_add_f32_e32 v125, v125, v125
	v_add_f32_e32 v126, v126, v126
	v_add_f32_e32 v127, v127, v127
	v_add_f32_e32 v128, v128, v128
	v_mul_f32_e32 v121, 0x3fb8aa3b, v121
	v_mul_f32_e32 v122, 0x3fb8aa3b, v122
	v_mul_f32_e32 v123, 0x3fb8aa3b, v123
	v_mul_f32_e32 v124, 0x3fb8aa3b, v124
	v_mul_f32_e32 v125, 0x3fb8aa3b, v125
	v_mul_f32_e32 v126, 0x3fb8aa3b, v126
	v_mul_f32_e32 v127, 0x3fb8aa3b, v127
	v_mul_f32_e32 v128, 0x3fb8aa3b, v128
	v_exp_f32_e32 v121, v121
	v_exp_f32_e32 v122, v122
	v_exp_f32_e32 v123, v123
	v_exp_f32_e32 v124, v124
	v_exp_f32_e32 v125, v125
	v_exp_f32_e32 v126, v126
	v_exp_f32_e32 v127, v127
	v_exp_f32_e32 v128, v128
	v_mul_f32_e32 v129, 0.5, v113
	v_mul_f32_e32 v130, 0.5, v114
	v_mul_f32_e32 v131, 0.5, v115
	v_mul_f32_e32 v132, 0.5, v116
	v_mul_f32_e32 v133, 0.5, v117
	v_mul_f32_e32 v134, 0.5, v118
	v_mul_f32_e32 v135, 0.5, v119
	v_mul_f32_e32 v138, 0.5, v120
	v_add_f32_e32 v121, 1.0, v121
	v_add_f32_e32 v122, 1.0, v122
	v_add_f32_e32 v123, 1.0, v123
	v_add_f32_e32 v124, 1.0, v124
	v_add_f32_e32 v125, 1.0, v125
	v_add_f32_e32 v126, 1.0, v126
	v_add_f32_e32 v127, 1.0, v127
	v_add_f32_e32 v128, 1.0, v128
	v_rcp_f32_e32 v121, v121
	v_rcp_f32_e32 v122, v122
	v_rcp_f32_e32 v123, v123
	v_rcp_f32_e32 v124, v124
	v_rcp_f32_e32 v125, v125
	v_rcp_f32_e32 v126, v126
	v_rcp_f32_e32 v127, v127
	v_rcp_f32_e32 v128, v128
	v_add_f32_e32 v0, v0, v64
	v_add_f32_e32 v1, v1, v64
	v_add_f32_e32 v2, v2, v64
	v_add_f32_e32 v3, v3, v64
	v_add_f32_e32 v4, v4, v64
	v_add_f32_e32 v5, v5, v64
	v_add_f32_e32 v6, v6, v64
	v_add_f32_e32 v7, v7, v64
	v_fma_f32 v121, v121, -2.0, 1.0
	v_fma_f32 v122, v122, -2.0, 1.0
	v_fma_f32 v123, v123, -2.0, 1.0
	v_fma_f32 v124, v124, -2.0, 1.0
	v_fma_f32 v125, v125, -2.0, 1.0
	v_fma_f32 v126, v126, -2.0, 1.0
	v_fma_f32 v127, v127, -2.0, 1.0
	v_fma_f32 v128, v128, -2.0, 1.0
	v_add_f32_e32 v121, 1.0, v121
	v_add_f32_e32 v122, 1.0, v122
	v_add_f32_e32 v123, 1.0, v123
	v_add_f32_e32 v124, 1.0, v124
	v_add_f32_e32 v125, 1.0, v125
	v_add_f32_e32 v126, 1.0, v126
	v_add_f32_e32 v127, 1.0, v127
	v_add_f32_e32 v128, 1.0, v128
	v_mul_f32_e32 v121, v129, v121
	v_mul_f32_e32 v122, v130, v122
	v_mul_f32_e32 v123, v131, v123
	v_mul_f32_e32 v124, v132, v124
	v_mul_f32_e32 v125, v133, v125
	v_mul_f32_e32 v126, v134, v126
	v_mul_f32_e32 v127, v135, v127
	v_mul_f32_e32 v128, v138, v128
	v_mul_f32_e32 v0, v0, v121
	v_mul_f32_e32 v1, v1, v122
	v_mul_f32_e32 v2, v2, v123
	v_mul_f32_e32 v3, v3, v124
	v_mul_f32_e32 v4, v4, v125
	v_mul_f32_e32 v5, v5, v126
	v_mul_f32_e32 v6, v6, v127
	v_mul_f32_e32 v7, v7, v128
	v_cvt_pk_bf16_f32 v140, v0, v1
	v_cvt_pk_bf16_f32 v141, v2, v3
	global_store_dwordx2 v[66:67], v[140:141], off offset:192
	v_cvt_pk_bf16_f32 v142, v4, v5
	v_cvt_pk_bf16_f32 v143, v6, v7
	global_store_dwordx2 v[66:67], v[142:143], off offset:208
	s_waitcnt vmcnt(14)
; __device__ __forceinline__ unsigned pk2(float lo, float hi) { return f2bf(lo) | (f2bf(hi) << 16); }
; __device__ __forceinline__ float gelu_tanh(float x) {
;     const float u = 0.7978845608028654f * (x + 0.044715f * x * x * x);
;     const float e = __expf(2.0f * u);
;     const float th = 1.0f - 2.0f * __builtin_amdgcn_rcpf(e + 1.0f);
;     return 0.5f * x * (1.0f + th);
; }
; __device__ __forceinline__ void gmlp_fast(KArgs ap, int l, LAS unsigned char* lds, const Ctx cx) {
;     ...
;             for (int ht = 0; ht < 4; ++ht)
; #pragma unroll
;                 for (int q4 = 0; q4 < 4; ++q4) { const u32x2 uu = *(const u32x2*)(zu + ht * 32 + 8 * q4);
;                     const float o0 = gelu_tanh(bflo(uu.x)) * (acc[ht][4 * q4] + bsv), o1 = gelu_tanh(bfhi(uu.x)) * (acc[ht][4 * q4 + 1] + bsv);
;                     const float o2 = gelu_tanh(bflo(uu.y)) * (acc[ht][4 * q4 + 2] + bsv), o3 = gelu_tanh(bfhi(uu.y)) * (acc[ht][4 * q4 + 3] + bsv);
;                     u32x2 w; w.x = pk2(o0, o1); w.y = pk2(o2, o3); *(u32x2*)(yo + ht * 32 + 8 * q4) = w; }
	v_lshlrev_b32_e32 v113, 16, v226
	v_and_b32_e32 v114, 0xffff0000, v226
	v_lshlrev_b32_e32 v115, 16, v227
	v_and_b32_e32 v116, 0xffff0000, v227
	v_lshlrev_b32_e32 v117, 16, v228
	v_and_b32_e32 v118, 0xffff0000, v228
	v_lshlrev_b32_e32 v119, 16, v229
	v_and_b32_e32 v120, 0xffff0000, v229
	v_mul_f32_e32 v121, 0x3d372713, v113
	v_mul_f32_e32 v122, 0x3d372713, v114
	v_mul_f32_e32 v123, 0x3d372713, v115
	v_mul_f32_e32 v124, 0x3d372713, v116
	v_mul_f32_e32 v125, 0x3d372713, v117
	v_mul_f32_e32 v126, 0x3d372713, v118
	v_mul_f32_e32 v127, 0x3d372713, v119
	v_mul_f32_e32 v128, 0x3d372713, v120
	v_mul_f32_e32 v121, v121, v113
	v_mul_f32_e32 v122, v122, v114
	v_mul_f32_e32 v123, v123, v115
	v_mul_f32_e32 v124, v124, v116
	v_mul_f32_e32 v125, v125, v117
	v_mul_f32_e32 v126, v126, v118
	v_mul_f32_e32 v127, v127, v119
	v_mul_f32_e32 v128, v128, v120
	v_fma_f32 v121, v121, v113, v113
	v_fma_f32 v122, v122, v114, v114
	v_fma_f32 v123, v123, v115, v115
	v_fma_f32 v124, v124, v116, v116
	v_fma_f32 v125, v125, v117, v117
	v_fma_f32 v126, v126, v118, v118
	v_fma_f32 v127, v127, v119, v119
	v_fma_f32 v128, v128, v120, v120
	v_mul_f32_e32 v121, 0x3f4c422a, v121
	v_mul_f32_e32 v122, 0x3f4c422a, v122
	v_mul_f32_e32 v123, 0x3f4c422a, v123
	v_mul_f32_e32 v124, 0x3f4c422a, v124
	v_mul_f32_e32 v125, 0x3f4c422a, v125
	v_mul_f32_e32 v126, 0x3f4c422a, v126
	v_mul_f32_e32 v127, 0x3f4c422a, v127
	v_mul_f32_e32 v128, 0x3f4c422a, v128
	v_add_f32_e32 v121, v121, v121
	v_add_f32_e32 v122, v122, v122
	v_add_f32_e32 v123, v123, v123
	v_add_f32_e32 v124, v124, v124
	v_add_f32_e32 v125, v125, v125
	v_add_f32_e32 v126, v126, v126
	v_add_f32_e32 v127, v127, v127
	v_add_f32_e32 v128, v128, v128
	v_mul_f32_e32 v121, 0x3fb8aa3b, v121
	v_mul_f32_e32 v122, 0x3fb8aa3b, v122
	v_mul_f32_e32 v123, 0x3fb8aa3b, v123
	v_mul_f32_e32 v124, 0x3fb8aa3b, v124
	v_mul_f32_e32 v125, 0x3fb8aa3b, v125
	v_mul_f32_e32 v126, 0x3fb8aa3b, v126
	v_mul_f32_e32 v127, 0x3fb8aa3b, v127
	v_mul_f32_e32 v128, 0x3fb8aa3b, v128
	v_exp_f32_e32 v121, v121
	v_exp_f32_e32 v122, v122
	v_exp_f32_e32 v123, v123
	v_exp_f32_e32 v124, v124
	v_exp_f32_e32 v125, v125
	v_exp_f32_e32 v126, v126
	v_exp_f32_e32 v127, v127
	v_exp_f32_e32 v128, v128
	v_mul_f32_e32 v129, 0.5, v113
	v_mul_f32_e32 v130, 0.5, v114
	v_mul_f32_e32 v131, 0.5, v115
	v_mul_f32_e32 v132, 0.5, v116
	v_mul_f32_e32 v133, 0.5, v117
	v_mul_f32_e32 v134, 0.5, v118
	v_mul_f32_e32 v135, 0.5, v119
	v_mul_f32_e32 v138, 0.5, v120
	v_add_f32_e32 v121, 1.0, v121
	v_add_f32_e32 v122, 1.0, v122
	v_add_f32_e32 v123, 1.0, v123
	v_add_f32_e32 v124, 1.0, v124
	v_add_f32_e32 v125, 1.0, v125
	v_add_f32_e32 v126, 1.0, v126
	v_add_f32_e32 v127, 1.0, v127
	v_add_f32_e32 v128, 1.0, v128
	v_rcp_f32_e32 v121, v121
	v_rcp_f32_e32 v122, v122
	v_rcp_f32_e32 v123, v123
	v_rcp_f32_e32 v124, v124
	v_rcp_f32_e32 v125, v125
	v_rcp_f32_e32 v126, v126
	v_rcp_f32_e32 v127, v127
	v_rcp_f32_e32 v128, v128
	v_add_f32_e32 v8, v8, v64
	v_add_f32_e32 v9, v9, v64
	v_add_f32_e32 v10, v10, v64
	v_add_f32_e32 v11, v11, v64
	v_add_f32_e32 v12, v12, v64
	v_add_f32_e32 v13, v13, v64
	v_add_f32_e32 v14, v14, v64
	v_add_f32_e32 v15, v15, v64
	v_fma_f32 v121, v121, -2.0, 1.0
	v_fma_f32 v122, v122, -2.0, 1.0
	v_fma_f32 v123, v123, -2.0, 1.0
	v_fma_f32 v124, v124, -2.0, 1.0
	v_fma_f32 v125, v125, -2.0, 1.0
	v_fma_f32 v126, v126, -2.0, 1.0
	v_fma_f32 v127, v127, -2.0, 1.0
	v_fma_f32 v128, v128, -2.0, 1.0
	v_add_f32_e32 v121, 1.0, v121
	v_add_f32_e32 v122, 1.0, v122
	v_add_f32_e32 v123, 1.0, v123
	v_add_f32_e32 v124, 1.0, v124
	v_add_f32_e32 v125, 1.0, v125
	v_add_f32_e32 v126, 1.0, v126
	v_add_f32_e32 v127, 1.0, v127
	v_add_f32_e32 v128, 1.0, v128
	v_mul_f32_e32 v121, v129, v121
	v_mul_f32_e32 v122, v130, v122
	v_mul_f32_e32 v123, v131, v123
	v_mul_f32_e32 v124, v132, v124
	v_mul_f32_e32 v125, v133, v125
	v_mul_f32_e32 v126, v134, v126
	v_mul_f32_e32 v127, v135, v127
	v_mul_f32_e32 v128, v138, v128
	v_mul_f32_e32 v8, v8, v121
	v_mul_f32_e32 v9, v9, v122
	v_mul_f32_e32 v10, v10, v123
	v_mul_f32_e32 v11, v11, v124
	v_mul_f32_e32 v12, v12, v125
	v_mul_f32_e32 v13, v13, v126
	v_mul_f32_e32 v14, v14, v127
	v_mul_f32_e32 v15, v15, v128
	v_cvt_pk_bf16_f32 v144, v8, v9
	v_cvt_pk_bf16_f32 v145, v10, v11
	global_store_dwordx2 v[66:67], v[144:145], off offset:224
	v_cvt_pk_bf16_f32 v146, v12, v13
	v_cvt_pk_bf16_f32 v147, v14, v15
	global_store_dwordx2 v[66:67], v[146:147], off offset:240
	s_cbranch_vccnz .LBB0_140
